# proj0 phase: half of each XCD's workgroups (odd slots) start ~9us later so their DMA-bound K-loops overlap the other half's store-bound epilogues
# speedup vs baseline: 1.0082x; 1.0082x over previous
.LBB0_141:
	s_or_b64 exec, exec, s[0:1]
	s_add_u32 s33, s28, 0x1c00000
	s_addc_u32 s24, s29, 0
	s_lshr_b32 s25, s30, 3
	s_cmpk_lt_u32 s94, 0x400
	s_cselect_b64 s[6:7], -1, 0
	s_cmpk_gt_u32 s94, 0x3ff
	s_waitcnt lgkmcnt(0)
	s_barrier
	s_cbranch_scc1 .LBB0_230
	s_bfe_u32 s26, s94, 0x10003
	s_cmp_lg_u32 s26, 1
	s_cbranch_scc1 .Ldesync0
	s_sleep 127
	s_sleep 127
.Ldesync0:
	s_add_u32 s26, s28, 0x800000
	v_readlane_b32 s0, v237, 19
	s_addc_u32 s27, s29, 0
	s_lshr_b32 s50, s94, 3
	s_and_b32 s51, s0, 56
	s_add_u32 s0, s28, 0x100000
	s_addc_u32 s1, s29, 0
	s_add_u32 s52, s28, 0x5c00000
	s_addc_u32 s53, s29, 0
	s_add_u32 s54, s28, 0x90000
	s_addc_u32 s55, s29, 0
	s_and_b32 s2, s94, 7
	s_lshl_b32 s56, s2, 17
	s_mov_b32 s9, 0
	v_mov_b32_e32 v129, 0
	s_mov_b64 s[10:11], 0x2000
	s_mov_b64 s[12:13], 0x4000
	s_mov_b64 s[14:15], 0x6000
	s_add_i32 s57, 0, 0x10000
	s_mov_b64 s[16:17], 0x1e04000
	s_mov_b64 s[18:19], 0x1e06000
	s_mov_b64 s[20:21], 0x884000
	s_mov_b64 s[22:23], 0x886000
	s_mov_b64 s[38:39], 0x1e00000
	s_mov_b64 s[40:41], 0x1e02000
	s_mov_b64 s[42:43], 0x880000
	s_mov_b64 s[44:45], 0x882000
	s_mov_b64 s[46:47], 0x80000
	s_mov_b64 s[48:49], 0x200000
	v_mov_b32_e32 v158, 0x3e38aa3b
	v_mbcnt_hi_u32_b32 v159, -1, v145
	s_mov_b32 s60, s50
	s_branch .LBB0_145
